# v64 + P5 attention: K-fragment and V^T-fragment LDS reads double-buffered against the MFMAs (QK: counted lgkmcnt(1) waits; PV: next group's transposed reads issued before the current group's MFMAs)
# speedup vs baseline: 1.0031x; 1.0031x over previous
; #define LAS __attribute__((address_space(3)))
; __device__ __forceinline__ void att_tile(const LAS unsigned char* kb, const LAS unsigned char* vb, int k0, int lq, int i, int hh, int troff,
;                                          const bf16x8 (&qf)[8], f32x16 (&oacc)[4], float& mrun, float& lrun) {
;     constexpr float SC = 0.08838834764831845f * 1.4426950408889634f;
;     f32x16 sacc, sacc2;
; #pragma unroll
;     for (int r = 0; r < 16; ++r) { sacc[r] = 0.f; sacc2[r] = 0.f; }
; #pragma unroll
;     for (int s = 0; s < 8; s += 2) { sacc = __builtin_amdgcn_mfma_f32_32x32x16_bf16(*(const LAS bf16x8*)(kb + i * 272 + 32 * s + 16 * hh), qf[s], sacc, 0, 0, 0);
;         sacc2 = __builtin_amdgcn_mfma_f32_32x32x16_bf16(*(const LAS bf16x8*)(kb + i * 272 + 32 * (s + 1) + 16 * hh), qf[s + 1], sacc2, 0, 0, 0); }
; #pragma unroll
;     for (int r = 0; r < 16; ++r) sacc[r] += sacc2[r];
;     float tmax = -1e30f;
;     const int dbase = lq - k0 - 4 * hh;
; #pragma unroll
;     for (int r = 0; r < 16; ++r) { const unsigned dd = (unsigned)(dbase - ((r & 3) + 8 * (r >> 2)));
;         const float sv = dd <= 128u ? sacc[r] * SC : -INFINITY; sacc[r] = sv; tmax = fmaxf(tmax, sv); }
;     { const u32x2 sw = __builtin_amdgcn_permlane32_swap(__float_as_uint(tmax), __float_as_uint(tmax), false, false); tmax = fmaxf(__uint_as_float(sw.x), __uint_as_float(sw.y)); }
;     const float mnew = fmaxf(mrun, tmax);
;     const float alpha = __builtin_amdgcn_exp2f(mrun - mnew);
; #pragma unroll
;     for (int dt = 0; dt < 4; ++dt)
; #pragma unroll
;         for (int r = 0; r < 16; ++r) oacc[dt][r] *= alpha;
.LBB0_660:
	s_or_b64 exec, exec, s[70:71]
	s_cmp_lt_u32 s72, s81
	s_cbranch_scc1 .LBB0_663
	s_cmp_lt_u32 s72, s82
	s_cselect_b64 s[66:67], -1, 0
	s_cmp_gt_i32 s59, -1
	s_cselect_b64 s[68:69], -1, 0
	s_and_b64 s[66:67], s[66:67], s[68:69]
	s_andn2_b64 vcc, exec, s[66:67]
	s_cbranch_vccnz .LBB0_663
	s_and_b32 s66, s72, 1
	s_or_b32 s66, s66, s79
	s_mulk_i32 s66, 0x4a00
	s_add_i32 s66, s66, 0
	v_add3_u32 v154, s66, v156, v169
	ds_read_b128 v[64:67], v154
	ds_read_b128 v[80:83], v154 offset:32
	ds_read_b128 v[170:173], v154 offset:64
	ds_read_b128 v[222:225], v154 offset:96
	s_waitcnt lgkmcnt(1)
	v_mfma_f32_32x32x16_bf16 v[64:79], v[64:67], v[96:99], 0
	v_mfma_f32_32x32x16_bf16 v[64:79], v[170:173], v[104:107], v[64:79]
	ds_read_b128 v[170:173], v154 offset:128
	v_mfma_f32_32x32x16_bf16 v[80:95], v[80:83], v[100:103], 0
	s_waitcnt lgkmcnt(1)
	v_mfma_f32_32x32x16_bf16 v[80:95], v[222:225], v[108:111], v[80:95]
	ds_read_b128 v[222:225], v154 offset:160
	s_waitcnt lgkmcnt(1)
	v_mfma_f32_32x32x16_bf16 v[64:79], v[170:173], v[112:115], v[64:79]
	ds_read_b128 v[170:173], v154 offset:192
	s_waitcnt lgkmcnt(1)
	v_mfma_f32_32x32x16_bf16 v[80:95], v[222:225], v[116:119], v[80:95]
	ds_read_b128 v[222:225], v154 offset:224
	s_waitcnt lgkmcnt(1)
	v_mfma_f32_32x32x16_bf16 v[64:79], v[170:173], v[120:123], v[64:79]
	s_waitcnt lgkmcnt(0)
	v_mfma_f32_32x32x16_bf16 v[80:95], v[222:225], v[124:127], v[80:95]
	s_nop 11
	v_add_f32_e32 v64, v64, v80
	v_add_u32_e32 v80, s57, v152
	v_add_f32_e32 v65, v65, v81
	v_add_u32_e32 v81, 0x80, v80
	v_cmp_gt_u32_e32 vcc, s87, v81
	v_mul_f32_e32 v64, 0x3e0293ee, v64
	v_add_f32_e32 v66, v66, v82
	v_cndmask_b32_e32 v81, v167, v64, vcc
	v_cmp_lt_u32_e32 vcc, s22, v153
	v_mul_f32_e32 v64, 0x3e0293ee, v65
	v_add_u32_e32 v82, 0x7e, v80
	v_cndmask_b32_e32 v65, v167, v64, vcc
	v_cmp_gt_u32_e32 vcc, s87, v82
	v_mul_f32_e32 v66, 0x3e0293ee, v66
	v_add_f32_e32 v67, v67, v83
	v_cndmask_b32_e32 v82, v167, v66, vcc
	v_add_u32_e32 v66, 0x7d, v80
	v_cmp_gt_u32_e32 vcc, s87, v66
	v_mul_f32_e32 v66, 0x3e0293ee, v67
	v_add_f32_e32 v68, v68, v84
	v_cndmask_b32_e32 v67, v167, v66, vcc
	v_add_u32_e32 v66, 0x78, v80
	v_cmp_gt_u32_e32 vcc, s87, v66
	v_mul_f32_e32 v66, 0x3e0293ee, v68
	v_add_f32_e32 v69, v69, v85
	v_cndmask_b32_e32 v68, v167, v66, vcc
	v_add_u32_e32 v66, 0x77, v80
	v_cmp_gt_u32_e32 vcc, s87, v66
	v_mul_f32_e32 v66, 0x3e0293ee, v69
	v_add_f32_e32 v70, v70, v86
	v_cndmask_b32_e32 v69, v167, v66, vcc
	v_add_u32_e32 v66, 0x76, v80
	v_cmp_gt_u32_e32 vcc, s87, v66
	v_mul_f32_e32 v66, 0x3e0293ee, v70
	v_add_f32_e32 v71, v71, v87
	v_cndmask_b32_e32 v70, v167, v66, vcc
	v_add_u32_e32 v66, 0x75, v80
	v_cmp_gt_u32_e32 vcc, s87, v66
	v_mul_f32_e32 v66, 0x3e0293ee, v71
	v_add_f32_e32 v72, v72, v88
	v_cndmask_b32_e32 v71, v167, v66, vcc
	v_add_u32_e32 v66, 0x70, v80
	v_cmp_gt_u32_e32 vcc, s87, v66
	v_mul_f32_e32 v66, 0x3e0293ee, v72
	v_add_f32_e32 v73, v73, v89
	v_cndmask_b32_e32 v72, v167, v66, vcc
	v_add_u32_e32 v66, 0x6f, v80
	v_cmp_gt_u32_e32 vcc, s87, v66
	v_mul_f32_e32 v66, 0x3e0293ee, v73
	v_add_f32_e32 v74, v74, v90
	v_cndmask_b32_e32 v73, v167, v66, vcc
	v_add_u32_e32 v66, 0x6e, v80
	v_cmp_gt_u32_e32 vcc, s87, v66
	v_mul_f32_e32 v66, 0x3e0293ee, v74
	v_add_f32_e32 v75, v75, v91
	v_cndmask_b32_e32 v74, v167, v66, vcc
	v_add_u32_e32 v66, 0x6d, v80
	v_cmp_gt_u32_e32 vcc, s87, v66
	v_mul_f32_e32 v66, 0x3e0293ee, v75
	v_add_f32_e32 v76, v76, v92
	v_cndmask_b32_e32 v75, v167, v66, vcc
	v_add_u32_e32 v66, 0x68, v80
	v_cmp_gt_u32_e32 vcc, s87, v66
	v_mul_f32_e32 v66, 0x3e0293ee, v76
	v_add_f32_e32 v77, v77, v93
	v_max3_f32 v64, v81, s23, v65
	v_cndmask_b32_e32 v76, v167, v66, vcc
	v_add_u32_e32 v66, 0x67, v80
	v_max3_f32 v64, v64, v82, v67
	v_cmp_gt_u32_e32 vcc, s87, v66
	v_mul_f32_e32 v66, 0x3e0293ee, v77
	v_add_f32_e32 v78, v78, v94
	v_max3_f32 v64, v64, v68, v69
	v_cndmask_b32_e32 v77, v167, v66, vcc
	v_add_u32_e32 v66, 0x66, v80
	v_max3_f32 v64, v64, v70, v71
	v_cmp_gt_u32_e32 vcc, s87, v66
	v_mul_f32_e32 v66, 0x3e0293ee, v78
	v_add_f32_e32 v79, v79, v95
	v_max3_f32 v64, v64, v72, v73
	v_cndmask_b32_e32 v78, v167, v66, vcc
	v_add_u32_e32 v66, 0x65, v80
	v_max3_f32 v64, v64, v74, v75
	v_cmp_gt_u32_e32 vcc, s87, v66
	v_mul_f32_e32 v66, 0x3e0293ee, v79
	v_max3_f32 v64, v64, v76, v77
	v_cndmask_b32_e32 v79, v167, v66, vcc
	v_max3_f32 v64, v64, v78, v79
	v_mov_b32_e32 v66, v64
	s_nop 1
	v_permlane32_swap_b32_e32 v64, v66
	v_max3_f32 v64, v148, v64, v66
	v_sub_f32_e32 v80, v81, v64
	v_exp_f32_e32 v80, v80
	v_sub_f32_e32 v65, v65, v64
	v_sub_f32_e32 v66, v148, v64
	v_exp_f32_e32 v83, v65
	v_exp_f32_e32 v66, v66
	v_add_f32_e32 v81, 0, v80
	v_sub_f32_e32 v68, v68, v64
	v_add_f32_e32 v65, v83, v81
	v_sub_f32_e32 v81, v82, v64
	v_pk_mul_f32 v[62:63], v[62:63], v[66:67] op_sel_hi:[1,0]
; #define LAS __attribute__((address_space(3)))
; __device__ __forceinline__ bf16x8 pack_step(const f32x16& x, int s) { u32x4 p; p.x = cvtpk_c(x[8 * s], x[8 * s + 1]); p.y = cvtpk_c(x[8 * s + 2], x[8 * s + 3]); p.z = cvtpk_c(x[8 * s + 4], x[8 * s + 5]); p.w = cvtpk_c(x[8 * s + 6], x[8 * s + 7]); return __builtin_bit_cast(bf16x8, p); }
; #define ATT_TR4(O0, O1, O2, O3) asm volatile("ds_read_b64_tr_b16 %0, %4 offset:" #O0 "\n\tds_read_b64_tr_b16 %1, %4 offset:" #O1 "\n\tds_read_b64_tr_b16 %2, %4 offset:" #O2 "\n\tds_read_b64_tr_b16 %3, %4 offset:" #O3 "\n\ts_waitcnt lgkmcnt(0)" \
;         : "=&v"(a0), "=&v"(a1), "=&v"(a2), "=&v"(a3) : "v"(vp) : "memory")
; #define ATT_PV(DT) do { const bf16x8 A0 = __builtin_shufflevector(a0, a1, 0, 1, 2, 3, 4, 5, 6, 7), A1 = __builtin_shufflevector(a2, a3, 0, 1, 2, 3, 4, 5, 6, 7); \
;         oacc[DT] = __builtin_amdgcn_mfma_f32_32x32x16_bf16(A0, pf0, oacc[DT], 0, 0, 0); oacc[DT] = __builtin_amdgcn_mfma_f32_32x32x16_bf16(A1, pf1, oacc[DT], 0, 0, 0); } while (0)
; __device__ __forceinline__ void att_tile(const LAS unsigned char* kb, const LAS unsigned char* vb, int k0, int lq, int i, int hh, int troff,
;                                          const bf16x8 (&qf)[8], f32x16 (&oacc)[4], float& mrun, float& lrun) {
;     ...
;     const float alpha = __builtin_amdgcn_exp2f(mrun - mnew);
; #pragma unroll
;     for (int dt = 0; dt < 4; ++dt)
; #pragma unroll
;         for (int r = 0; r < 16; ++r) oacc[dt][r] *= alpha;
;     float psum = 0.f;
; #pragma unroll
;     for (int r = 0; r < 16; ++r) { const float p = __builtin_amdgcn_exp2f(sacc[r] - mnew); sacc[r] = p; psum += p; }
;     { const u32x2 sw = __builtin_amdgcn_permlane32_swap(__float_as_uint(psum), __float_as_uint(psum), false, false); psum = __uint_as_float(sw.x) + __uint_as_float(sw.y); }
;     lrun = lrun * alpha + psum; mrun = mnew;
;     const bf16x8 pf0 = pack_step(sacc, 0), pf1 = pack_step(sacc, 1);
;     { const LAS unsigned char* vp = vb + troff;
;       v4i16_t a0, a1, a2, a3;
;     ...
;       ATT_TR4(0, 2560, 5120, 7680); ATT_PV(0);
;       ATT_TR4(64, 2624, 5184, 7744); ATT_PV(1);
;       ATT_TR4(128, 2688, 5248, 7808); ATT_PV(2);
;       ATT_TR4(192, 2752, 5312, 7872); ATT_PV(3);
	v_pk_mul_f32 v[60:61], v[60:61], v[66:67] op_sel_hi:[1,0]
	v_pk_mul_f32 v[58:59], v[58:59], v[66:67] op_sel_hi:[1,0]
	v_pk_mul_f32 v[56:57], v[56:57], v[66:67] op_sel_hi:[1,0]
	v_pk_mul_f32 v[54:55], v[54:55], v[66:67] op_sel_hi:[1,0]
	v_pk_mul_f32 v[52:53], v[52:53], v[66:67] op_sel_hi:[1,0]
	v_pk_mul_f32 v[50:51], v[50:51], v[66:67] op_sel_hi:[1,0]
	v_pk_mul_f32 v[48:49], v[48:49], v[66:67] op_sel_hi:[1,0]
	v_pk_mul_f32 v[46:47], v[46:47], v[66:67] op_sel_hi:[1,0]
	v_pk_mul_f32 v[44:45], v[44:45], v[66:67] op_sel_hi:[1,0]
	v_pk_mul_f32 v[42:43], v[42:43], v[66:67] op_sel_hi:[1,0]
	v_pk_mul_f32 v[40:41], v[40:41], v[66:67] op_sel_hi:[1,0]
	v_pk_mul_f32 v[38:39], v[38:39], v[66:67] op_sel_hi:[1,0]
	v_pk_mul_f32 v[36:37], v[36:37], v[66:67] op_sel_hi:[1,0]
	v_pk_mul_f32 v[34:35], v[34:35], v[66:67] op_sel_hi:[1,0]
	v_pk_mul_f32 v[32:33], v[32:33], v[66:67] op_sel_hi:[1,0]
	v_pk_mul_f32 v[30:31], v[30:31], v[66:67] op_sel_hi:[1,0]
	v_pk_mul_f32 v[28:29], v[28:29], v[66:67] op_sel_hi:[1,0]
	v_pk_mul_f32 v[26:27], v[26:27], v[66:67] op_sel_hi:[1,0]
	v_pk_mul_f32 v[24:25], v[24:25], v[66:67] op_sel_hi:[1,0]
	v_pk_mul_f32 v[22:23], v[22:23], v[66:67] op_sel_hi:[1,0]
	v_pk_mul_f32 v[20:21], v[20:21], v[66:67] op_sel_hi:[1,0]
	v_pk_mul_f32 v[18:19], v[18:19], v[66:67] op_sel_hi:[1,0]
	v_pk_mul_f32 v[16:17], v[16:17], v[66:67] op_sel_hi:[1,0]
	v_pk_mul_f32 v[14:15], v[14:15], v[66:67] op_sel_hi:[1,0]
	v_pk_mul_f32 v[12:13], v[12:13], v[66:67] op_sel_hi:[1,0]
	v_pk_mul_f32 v[10:11], v[10:11], v[66:67] op_sel_hi:[1,0]
	v_pk_mul_f32 v[8:9], v[8:9], v[66:67] op_sel_hi:[1,0]
	v_pk_mul_f32 v[6:7], v[6:7], v[66:67] op_sel_hi:[1,0]
	v_pk_mul_f32 v[4:5], v[4:5], v[66:67] op_sel_hi:[1,0]
	v_pk_mul_f32 v[2:3], v[2:3], v[66:67] op_sel_hi:[1,0]
	v_pk_mul_f32 v[0:1], v[0:1], v[66:67] op_sel_hi:[1,0]
	v_exp_f32_e32 v81, v81
	v_sub_f32_e32 v67, v67, v64
	v_exp_f32_e32 v67, v67
	v_exp_f32_e32 v68, v68
	v_sub_f32_e32 v69, v69, v64
	v_exp_f32_e32 v69, v69
	v_sub_f32_e32 v70, v70, v64
	v_add_f32_e32 v65, v81, v65
	v_exp_f32_e32 v70, v70
	v_sub_f32_e32 v71, v71, v64
	v_add_f32_e32 v65, v67, v65
	v_exp_f32_e32 v71, v71
	v_sub_f32_e32 v72, v72, v64
	v_add_f32_e32 v65, v68, v65
	v_exp_f32_e32 v72, v72
	v_sub_f32_e32 v73, v73, v64
	v_add_f32_e32 v65, v69, v65
	v_exp_f32_e32 v73, v73
	v_sub_f32_e32 v74, v74, v64
	v_add_f32_e32 v65, v70, v65
	v_exp_f32_e32 v74, v74
	v_sub_f32_e32 v75, v75, v64
	v_add_f32_e32 v65, v71, v65
	v_exp_f32_e32 v75, v75
	v_sub_f32_e32 v76, v76, v64
	v_add_f32_e32 v65, v72, v65
	v_exp_f32_e32 v76, v76
	v_sub_f32_e32 v77, v77, v64
	v_add_f32_e32 v65, v73, v65
	v_exp_f32_e32 v77, v77
	v_sub_f32_e32 v78, v78, v64
	v_add_f32_e32 v65, v74, v65
	v_exp_f32_e32 v78, v78
	v_sub_f32_e32 v79, v79, v64
	v_add_f32_e32 v65, v75, v65
	v_exp_f32_e32 v79, v79
	v_add_f32_e32 v65, v76, v65
	v_add_f32_e32 v65, v77, v65
	v_add_f32_e32 v65, v78, v65
	v_add_f32_e32 v65, v79, v65
	v_mov_b32_e32 v82, v65
	s_nop 1
	v_permlane32_swap_b32_e32 v65, v82
	v_add_f32_e32 v65, v65, v82
	v_fmac_f32_e32 v65, v149, v66
	v_cvt_pk_bf16_f32 v66, v80, v83
	v_cvt_pk_bf16_f32 v67, v81, v67
	v_cvt_pk_bf16_f32 v68, v68, v69
	v_cvt_pk_bf16_f32 v69, v70, v71
	v_cvt_pk_bf16_f32 v71, v74, v75
	v_add_u32_e32 v74, s66, v159
	v_cvt_pk_bf16_f32 v70, v72, v73
	v_cvt_pk_bf16_f32 v72, v76, v77
	v_cvt_pk_bf16_f32 v73, v78, v79
	v_add_u32_e32 v82, 0x2200, v74
	ds_read_b64_tr_b16 v[78:79], v82 offset:0
	ds_read_b64_tr_b16 v[80:81], v82 offset:2560
	ds_read_b64_tr_b16 v[74:75], v82 offset:5120
	ds_read_b64_tr_b16 v[76:77], v82 offset:7680
	ds_read_b64_tr_b16 v[214:215], v82 offset:64
	ds_read_b64_tr_b16 v[216:217], v82 offset:2624
	ds_read_b64_tr_b16 v[218:219], v82 offset:5184
	ds_read_b64_tr_b16 v[220:221], v82 offset:7744
	s_waitcnt lgkmcnt(4)
	v_mov_b32_e32 v149, v65
	v_mfma_f32_32x32x16_bf16 v[48:63], v[78:81], v[66:69], v[48:63]
	v_mov_b32_e32 v148, v64
	v_mfma_f32_32x32x16_bf16 v[48:63], v[74:77], v[70:73], v[48:63]
	ds_read_b64_tr_b16 v[78:79], v82 offset:128
	ds_read_b64_tr_b16 v[80:81], v82 offset:2688
	ds_read_b64_tr_b16 v[74:75], v82 offset:5248
	ds_read_b64_tr_b16 v[76:77], v82 offset:7808
	s_waitcnt lgkmcnt(4)
	s_nop 0
	v_mfma_f32_32x32x16_bf16 v[32:47], v[214:217], v[66:69], v[32:47]
	v_mfma_f32_32x32x16_bf16 v[32:47], v[218:221], v[70:73], v[32:47]
	ds_read_b64_tr_b16 v[214:215], v82 offset:192
	ds_read_b64_tr_b16 v[216:217], v82 offset:2752
	ds_read_b64_tr_b16 v[218:219], v82 offset:5312
	ds_read_b64_tr_b16 v[220:221], v82 offset:7872
	s_waitcnt lgkmcnt(4)
	s_nop 0
	v_mfma_f32_32x32x16_bf16 v[16:31], v[78:81], v[66:69], v[16:31]
	v_mfma_f32_32x32x16_bf16 v[16:31], v[74:77], v[70:73], v[16:31]
	s_waitcnt lgkmcnt(0)
	s_nop 0
	v_mfma_f32_32x32x16_bf16 v[0:15], v[214:217], v[66:69], v[0:15]
	v_mfma_f32_32x32x16_bf16 v[0:15], v[218:221], v[70:73], v[0:15]
	s_branch .LBB0_664

; #define LAS __attribute__((address_space(3)))
; __device__ __forceinline__ void att_tile(const LAS unsigned char* kb, const LAS unsigned char* vb, int k0, int lq, int i, int hh, int troff,
;                                          const bf16x8 (&qf)[8], f32x16 (&oacc)[4], float& mrun, float& lrun) {
;     constexpr float SC = 0.08838834764831845f * 1.4426950408889634f;
;     f32x16 sacc, sacc2;
; #pragma unroll
;     for (int r = 0; r < 16; ++r) { sacc[r] = 0.f; sacc2[r] = 0.f; }
; #pragma unroll
;     for (int s = 0; s < 8; s += 2) { sacc = __builtin_amdgcn_mfma_f32_32x32x16_bf16(*(const LAS bf16x8*)(kb + i * 272 + 32 * s + 16 * hh), qf[s], sacc, 0, 0, 0);
;         sacc2 = __builtin_amdgcn_mfma_f32_32x32x16_bf16(*(const LAS bf16x8*)(kb + i * 272 + 32 * (s + 1) + 16 * hh), qf[s + 1], sacc2, 0, 0, 0); }
; #pragma unroll
;     for (int r = 0; r < 16; ++r) sacc[r] += sacc2[r];
;     float tmax = -1e30f;
;     const int dbase = lq - k0 - 4 * hh;
; #pragma unroll
;     for (int r = 0; r < 16; ++r) { const unsigned dd = (unsigned)(dbase - ((r & 3) + 8 * (r >> 2)));
;         const float sv = dd <= 128u ? sacc[r] * SC : -INFINITY; sacc[r] = sv; tmax = fmaxf(tmax, sv); }
;     { const u32x2 sw = __builtin_amdgcn_permlane32_swap(__float_as_uint(tmax), __float_as_uint(tmax), false, false); tmax = fmaxf(__uint_as_float(sw.x), __uint_as_float(sw.y)); }
;     const float mnew = fmaxf(mrun, tmax);
;     const float alpha = __builtin_amdgcn_exp2f(mrun - mnew);
; #pragma unroll
;     for (int dt = 0; dt < 4; ++dt)
; #pragma unroll
;         for (int r = 0; r < 16; ++r) oacc[dt][r] *= alpha;
; __device__ __forceinline__ void attn_wg(const bf16* PROJ, bf16* CONCAT, int wu, LAS unsigned char* L, int tid, int lane, int wave) {
;     ...
;       for (int j = 0; j < nt; ++j) {
;           const bool more = j + 1 < nt;
;           if (more) { int tok = ((kB + 32 * (j + 1) + row) << 2) + rd; tok = tok < SEQ - 1 ? tok : SEQ - 1; const bf16* kp = kbase + (size_t)tok * LDP + 8 * ch; const bf16* vp = vbase + (size_t)tok * LDP + 8 * ch;
;               kr0 = *(const u32x4*)kp; kr1 = *(const u32x4*)(kp + 8); vr0 = *(const u32x4*)vp; vr1 = *(const u32x4*)(vp + 8); }
;           const LAS unsigned char* tb = gb + (j & 1) * TILE;
;           att_tile(tb, tb + ATT_KS_BYTES, kB + 32 * j, lq, i, hh, troff, qf, oacc, mrun, lrun);
.LBB0_672:
	s_add_i32 s21, s52, 1
	s_bitcmp1_b32 s52, 0
	s_cselect_b32 s52, 0x4a00, 0
	s_add_i32 s52, s84, s52
	v_add3_u32 v147, s52, v156, v169
	ds_read_b128 v[64:67], v147
	ds_read_b128 v[80:83], v147 offset:32
	ds_read_b128 v[176:179], v147 offset:64
	ds_read_b128 v[222:225], v147 offset:96
	s_waitcnt lgkmcnt(1)
	v_mfma_f32_32x32x16_bf16 v[64:79], v[64:67], v[96:99], 0
	v_mfma_f32_32x32x16_bf16 v[64:79], v[176:179], v[104:107], v[64:79]
	ds_read_b128 v[176:179], v147 offset:128
	v_mfma_f32_32x32x16_bf16 v[80:95], v[80:83], v[100:103], 0
	s_waitcnt lgkmcnt(1)
	v_mfma_f32_32x32x16_bf16 v[80:95], v[222:225], v[108:111], v[80:95]
	ds_read_b128 v[222:225], v147 offset:160
	s_waitcnt lgkmcnt(1)
	v_mfma_f32_32x32x16_bf16 v[64:79], v[176:179], v[112:115], v[64:79]
	ds_read_b128 v[176:179], v147 offset:192
	s_waitcnt lgkmcnt(1)
	v_mfma_f32_32x32x16_bf16 v[80:95], v[222:225], v[116:119], v[80:95]
	ds_read_b128 v[222:225], v147 offset:224
	s_waitcnt lgkmcnt(1)
	v_mfma_f32_32x32x16_bf16 v[64:79], v[176:179], v[120:123], v[64:79]
	s_waitcnt lgkmcnt(0)
	v_mfma_f32_32x32x16_bf16 v[80:95], v[222:225], v[124:127], v[80:95]
	s_nop 11
	v_add_f32_e32 v64, v64, v80
	v_add_u32_e32 v80, 27, v160
	v_add_f32_e32 v65, v65, v81
	v_cmp_gt_u32_e32 vcc, s87, v80
	v_mul_f32_e32 v64, 0x3e0293ee, v64
	v_add_f32_e32 v66, v66, v82
	v_cndmask_b32_e32 v80, v167, v64, vcc
	v_cmp_lt_u32_e32 vcc, s22, v173
	v_mul_f32_e32 v64, 0x3e0293ee, v65
	v_add_u32_e32 v81, 25, v160
	v_add_f32_e32 v67, v67, v83
	v_cndmask_b32_e32 v65, v167, v64, vcc
	v_cmp_gt_u32_e32 vcc, s87, v81
	v_mul_f32_e32 v66, 0x3e0293ee, v66
	v_add_u32_e32 v81, 24, v160
	v_add_f32_e32 v68, v68, v84
	v_cndmask_b32_e32 v66, v167, v66, vcc
	v_cmp_gt_u32_e32 vcc, s87, v81
	v_mul_f32_e32 v67, 0x3e0293ee, v67
	v_add_u32_e32 v81, 19, v160
	v_add_f32_e32 v69, v69, v85
	v_cndmask_b32_e32 v67, v167, v67, vcc
	v_cmp_gt_u32_e32 vcc, s87, v81
	v_mul_f32_e32 v68, 0x3e0293ee, v68
	v_add_u32_e32 v81, 18, v160
	v_add_f32_e32 v70, v70, v86
	v_cndmask_b32_e32 v68, v167, v68, vcc
	v_cmp_gt_u32_e32 vcc, s87, v81
	v_mul_f32_e32 v69, 0x3e0293ee, v69
	v_add_u32_e32 v81, 17, v160
	v_add_f32_e32 v71, v71, v87
	v_cndmask_b32_e32 v69, v167, v69, vcc
	v_cmp_gt_u32_e32 vcc, s87, v81
	v_mul_f32_e32 v70, 0x3e0293ee, v70
	v_add_u32_e32 v81, 16, v160
	v_add_f32_e32 v72, v72, v88
	v_cndmask_b32_e32 v70, v167, v70, vcc
	v_cmp_gt_u32_e32 vcc, s87, v81
	v_mul_f32_e32 v71, 0x3e0293ee, v71
	v_add_u32_e32 v81, 11, v160
	v_add_f32_e32 v73, v73, v89
	v_cndmask_b32_e32 v71, v167, v71, vcc
	v_cmp_gt_u32_e32 vcc, s87, v81
	v_mul_f32_e32 v72, 0x3e0293ee, v72
	v_add_u32_e32 v81, 10, v160
	v_add_f32_e32 v74, v74, v90
	v_cndmask_b32_e32 v72, v167, v72, vcc
	v_cmp_gt_u32_e32 vcc, s87, v81
	v_mul_f32_e32 v73, 0x3e0293ee, v73
	v_add_u32_e32 v81, 9, v160
	v_add_f32_e32 v75, v75, v91
	v_max3_f32 v64, v80, s23, v65
	v_cndmask_b32_e32 v73, v167, v73, vcc
	v_cmp_gt_u32_e32 vcc, s87, v81
	v_mul_f32_e32 v74, 0x3e0293ee, v74
	v_add_u32_e32 v81, 8, v160
	v_add_f32_e32 v76, v76, v92
	v_max3_f32 v64, v64, v66, v67
	v_cndmask_b32_e32 v74, v167, v74, vcc
	v_cmp_gt_u32_e32 vcc, s87, v81
	v_mul_f32_e32 v75, 0x3e0293ee, v75
	v_add_u32_e32 v81, 3, v160
	v_add_f32_e32 v77, v77, v93
	v_max3_f32 v64, v64, v68, v69
	v_cndmask_b32_e32 v75, v167, v75, vcc
	v_cmp_gt_u32_e32 vcc, s87, v81
	v_mul_f32_e32 v76, 0x3e0293ee, v76
	v_add_u32_e32 v81, 2, v160
	v_add_f32_e32 v78, v78, v94
	v_max3_f32 v64, v64, v70, v71
	v_cndmask_b32_e32 v76, v167, v76, vcc
	v_cmp_gt_u32_e32 vcc, s87, v81
	v_mul_f32_e32 v77, 0x3e0293ee, v77
	v_add_u32_e32 v81, 1, v160
	v_add_f32_e32 v79, v79, v95
	v_max3_f32 v64, v64, v72, v73
	v_cndmask_b32_e32 v77, v167, v77, vcc
	v_cmp_gt_u32_e32 vcc, s87, v81
	v_mul_f32_e32 v78, 0x3e0293ee, v78
	v_max3_f32 v64, v64, v74, v75
	v_cndmask_b32_e32 v78, v167, v78, vcc
	v_cmp_gt_u32_e32 vcc, s87, v160
	v_mul_f32_e32 v79, 0x3e0293ee, v79
	v_max3_f32 v64, v64, v76, v77
	v_cndmask_b32_e32 v79, v167, v79, vcc
	v_max3_f32 v64, v64, v78, v79
	v_mov_b32_e32 v81, v64
	s_nop 1
	v_permlane32_swap_b32_e32 v64, v81
	v_max3_f32 v170, v148, v64, v81
	v_sub_f32_e32 v64, v148, v170
	v_exp_f32_e32 v64, v64
	v_sub_f32_e32 v80, v80, v170
	v_exp_f32_e32 v80, v80
	v_sub_f32_e32 v66, v66, v170
	v_pk_mul_f32 v[62:63], v[62:63], v[64:65] op_sel_hi:[1,0]
	v_pk_mul_f32 v[60:61], v[60:61], v[64:65] op_sel_hi:[1,0]
	v_pk_mul_f32 v[58:59], v[58:59], v[64:65] op_sel_hi:[1,0]
	v_pk_mul_f32 v[56:57], v[56:57], v[64:65] op_sel_hi:[1,0]
	v_pk_mul_f32 v[54:55], v[54:55], v[64:65] op_sel_hi:[1,0]
	v_pk_mul_f32 v[52:53], v[52:53], v[64:65] op_sel_hi:[1,0]
	v_pk_mul_f32 v[50:51], v[50:51], v[64:65] op_sel_hi:[1,0]
	v_pk_mul_f32 v[48:49], v[48:49], v[64:65] op_sel_hi:[1,0]
	v_pk_mul_f32 v[46:47], v[46:47], v[64:65] op_sel_hi:[1,0]
; #define LAS __attribute__((address_space(3)))
; __device__ __forceinline__ bf16x8 pack_step(const f32x16& x, int s) { u32x4 p; p.x = cvtpk_c(x[8 * s], x[8 * s + 1]); p.y = cvtpk_c(x[8 * s + 2], x[8 * s + 3]); p.z = cvtpk_c(x[8 * s + 4], x[8 * s + 5]); p.w = cvtpk_c(x[8 * s + 6], x[8 * s + 7]); return __builtin_bit_cast(bf16x8, p); }
; #define ATT_TR4(O0, O1, O2, O3) asm volatile("ds_read_b64_tr_b16 %0, %4 offset:" #O0 "\n\tds_read_b64_tr_b16 %1, %4 offset:" #O1 "\n\tds_read_b64_tr_b16 %2, %4 offset:" #O2 "\n\tds_read_b64_tr_b16 %3, %4 offset:" #O3 "\n\ts_waitcnt lgkmcnt(0)" \
;         : "=&v"(a0), "=&v"(a1), "=&v"(a2), "=&v"(a3) : "v"(vp) : "memory")
; __device__ __forceinline__ void att_tile(const LAS unsigned char* kb, const LAS unsigned char* vb, int k0, int lq, int i, int hh, int troff,
;                                          const bf16x8 (&qf)[8], f32x16 (&oacc)[4], float& mrun, float& lrun) {
;     ...
;     const float alpha = __builtin_amdgcn_exp2f(mrun - mnew);
; #pragma unroll
;     for (int dt = 0; dt < 4; ++dt)
; #pragma unroll
;         for (int r = 0; r < 16; ++r) oacc[dt][r] *= alpha;
;     float psum = 0.f;
; #pragma unroll
;     for (int r = 0; r < 16; ++r) { const float p = __builtin_amdgcn_exp2f(sacc[r] - mnew); sacc[r] = p; psum += p; }
;     { const u32x2 sw = __builtin_amdgcn_permlane32_swap(__float_as_uint(psum), __float_as_uint(psum), false, false); psum = __uint_as_float(sw.x) + __uint_as_float(sw.y); }
;     lrun = lrun * alpha + psum; mrun = mnew;
;     const bf16x8 pf0 = pack_step(sacc, 0), pf1 = pack_step(sacc, 1);
;     { const LAS unsigned char* vp = vb + troff;
;       v4i16_t a0, a1, a2, a3;
;     ...
;       ATT_TR4(0, 2560, 5120, 7680); ATT_PV(0);
;       ATT_TR4(64, 2624, 5184, 7744); ATT_PV(1);
;       ATT_TR4(128, 2688, 5248, 7808); ATT_PV(2);
;       ATT_TR4(192, 2752, 5312, 7872); ATT_PV(3);
; __device__ __forceinline__ void attn_wg(const bf16* PROJ, bf16* CONCAT, int wu, LAS unsigned char* L, int tid, int lane, int wave) {
;     ...
;           if (more) { LAS unsigned char* nb = gb + ((j + 1) & 1) * TILE; LAS u32x4* kd = (LAS u32x4*)(nb + row * 272 + 16 * ch); kd[0] = kr0; kd[1] = kr1;
;               LAS u32x4* vd = (LAS u32x4*)(nb + ATT_KS_BYTES + row * 320 + 16 * ch); vd[0] = vr0; vd[1] = vr1; }
	v_pk_mul_f32 v[44:45], v[44:45], v[64:65] op_sel_hi:[1,0]
	v_pk_mul_f32 v[42:43], v[42:43], v[64:65] op_sel_hi:[1,0]
	v_pk_mul_f32 v[40:41], v[40:41], v[64:65] op_sel_hi:[1,0]
	v_pk_mul_f32 v[38:39], v[38:39], v[64:65] op_sel_hi:[1,0]
	v_pk_mul_f32 v[36:37], v[36:37], v[64:65] op_sel_hi:[1,0]
	v_pk_mul_f32 v[34:35], v[34:35], v[64:65] op_sel_hi:[1,0]
	v_pk_mul_f32 v[32:33], v[32:33], v[64:65] op_sel_hi:[1,0]
	v_pk_mul_f32 v[30:31], v[30:31], v[64:65] op_sel_hi:[1,0]
	v_pk_mul_f32 v[28:29], v[28:29], v[64:65] op_sel_hi:[1,0]
	v_pk_mul_f32 v[26:27], v[26:27], v[64:65] op_sel_hi:[1,0]
	v_pk_mul_f32 v[24:25], v[24:25], v[64:65] op_sel_hi:[1,0]
	v_pk_mul_f32 v[22:23], v[22:23], v[64:65] op_sel_hi:[1,0]
	v_pk_mul_f32 v[20:21], v[20:21], v[64:65] op_sel_hi:[1,0]
	v_pk_mul_f32 v[18:19], v[18:19], v[64:65] op_sel_hi:[1,0]
	v_pk_mul_f32 v[16:17], v[16:17], v[64:65] op_sel_hi:[1,0]
	v_pk_mul_f32 v[14:15], v[14:15], v[64:65] op_sel_hi:[1,0]
	v_pk_mul_f32 v[12:13], v[12:13], v[64:65] op_sel_hi:[1,0]
	v_pk_mul_f32 v[10:11], v[10:11], v[64:65] op_sel_hi:[1,0]
	v_pk_mul_f32 v[8:9], v[8:9], v[64:65] op_sel_hi:[1,0]
	v_pk_mul_f32 v[6:7], v[6:7], v[64:65] op_sel_hi:[1,0]
	v_pk_mul_f32 v[4:5], v[4:5], v[64:65] op_sel_hi:[1,0]
	v_pk_mul_f32 v[2:3], v[2:3], v[64:65] op_sel_hi:[1,0]
	v_pk_mul_f32 v[0:1], v[0:1], v[64:65] op_sel_hi:[1,0]
	v_sub_f32_e32 v65, v65, v170
	v_exp_f32_e32 v82, v65
	v_add_f32_e32 v81, 0, v80
	s_andn2_b64 vcc, exec, s[4:5]
	v_add_f32_e32 v65, v82, v81
	v_exp_f32_e32 v81, v66
	v_sub_f32_e32 v66, v67, v170
	v_exp_f32_e32 v67, v66
	v_sub_f32_e32 v66, v68, v170
	v_exp_f32_e32 v83, v66
	v_sub_f32_e32 v66, v69, v170
	v_exp_f32_e32 v84, v66
	v_sub_f32_e32 v66, v70, v170
	v_add_f32_e32 v65, v81, v65
	v_exp_f32_e32 v85, v66
	v_sub_f32_e32 v66, v71, v170
	v_add_f32_e32 v65, v67, v65
	v_exp_f32_e32 v71, v66
	v_sub_f32_e32 v66, v72, v170
	v_add_f32_e32 v65, v83, v65
	v_exp_f32_e32 v72, v66
	v_sub_f32_e32 v66, v73, v170
	v_add_f32_e32 v65, v84, v65
	v_exp_f32_e32 v73, v66
	v_sub_f32_e32 v66, v74, v170
	v_add_f32_e32 v65, v85, v65
	v_exp_f32_e32 v74, v66
	v_sub_f32_e32 v66, v75, v170
	v_add_f32_e32 v65, v71, v65
	v_exp_f32_e32 v75, v66
	v_sub_f32_e32 v66, v76, v170
	v_add_f32_e32 v65, v72, v65
	v_exp_f32_e32 v76, v66
	v_sub_f32_e32 v66, v77, v170
	v_add_f32_e32 v65, v73, v65
	v_exp_f32_e32 v77, v66
	v_sub_f32_e32 v66, v78, v170
	v_add_f32_e32 v65, v74, v65
	v_exp_f32_e32 v78, v66
	v_sub_f32_e32 v66, v79, v170
	v_add_f32_e32 v65, v75, v65
	v_exp_f32_e32 v79, v66
	v_add_f32_e32 v65, v76, v65
	v_add_f32_e32 v65, v77, v65
	v_add_f32_e32 v65, v78, v65
	v_cvt_pk_bf16_f32 v68, v80, v82
	v_cvt_pk_bf16_f32 v69, v81, v67
	v_cvt_pk_bf16_f32 v70, v83, v84
	v_cvt_pk_bf16_f32 v71, v85, v71
	v_add_u32_e32 v67, s52, v159
	v_add_f32_e32 v65, v79, v65
	v_cvt_pk_bf16_f32 v72, v72, v73
	v_cvt_pk_bf16_f32 v73, v74, v75
	v_cvt_pk_bf16_f32 v74, v76, v77
	v_cvt_pk_bf16_f32 v75, v78, v79
	v_add_u32_e32 v67, 0x2200, v67
	ds_read_b64_tr_b16 v[80:81], v67 offset:0
	ds_read_b64_tr_b16 v[82:83], v67 offset:2560
	ds_read_b64_tr_b16 v[76:77], v67 offset:5120
	ds_read_b64_tr_b16 v[78:79], v67 offset:7680
	ds_read_b64_tr_b16 v[214:215], v67 offset:64
	ds_read_b64_tr_b16 v[216:217], v67 offset:2624
	ds_read_b64_tr_b16 v[218:219], v67 offset:5184
	ds_read_b64_tr_b16 v[220:221], v67 offset:7744
	s_waitcnt lgkmcnt(4)
	v_mov_b32_e32 v66, v65
	v_mfma_f32_32x32x16_bf16 v[48:63], v[80:83], v[68:71], v[48:63]
	s_nop 0
	v_permlane32_swap_b32_e32 v65, v66
	v_mfma_f32_32x32x16_bf16 v[48:63], v[76:79], v[72:75], v[48:63]
	ds_read_b64_tr_b16 v[80:81], v67 offset:128
	ds_read_b64_tr_b16 v[82:83], v67 offset:2688
	ds_read_b64_tr_b16 v[76:77], v67 offset:5248
	ds_read_b64_tr_b16 v[78:79], v67 offset:7808
	s_waitcnt lgkmcnt(4)
	s_nop 0
	v_mfma_f32_32x32x16_bf16 v[32:47], v[214:217], v[68:71], v[32:47]
	v_mfma_f32_32x32x16_bf16 v[32:47], v[218:221], v[72:75], v[32:47]
	ds_read_b64_tr_b16 v[214:215], v67 offset:192
	ds_read_b64_tr_b16 v[216:217], v67 offset:2752
	ds_read_b64_tr_b16 v[218:219], v67 offset:5312
	ds_read_b64_tr_b16 v[220:221], v67 offset:7872
	s_waitcnt lgkmcnt(4)
	s_nop 0
	v_mfma_f32_32x32x16_bf16 v[16:31], v[80:83], v[68:71], v[16:31]
	v_mfma_f32_32x32x16_bf16 v[16:31], v[76:79], v[72:75], v[16:31]
	s_waitcnt lgkmcnt(0)
	s_nop 0
	v_mfma_f32_32x32x16_bf16 v[0:15], v[214:217], v[68:71], v[0:15]
	v_mfma_f32_32x32x16_bf16 v[0:15], v[218:221], v[72:75], v[0:15]
	s_cbranch_vccnz .LBB0_674
	s_bitcmp1_b32 s21, 0
	s_cselect_b32 s4, 0x4a00, 0
	s_add_i32 s4, s84, s4
	v_add3_u32 v67, s4, v171, v146
	v_add3_u32 v68, s4, v172, v146
	s_waitcnt vmcnt(2)
	ds_write_b128 v67, v[132:135]
	ds_write_b128 v67, v[128:131] offset:16
	s_waitcnt vmcnt(0)
	ds_write_b128 v68, v[136:139] offset:8704
	ds_write_b128 v68, v[140:143] offset:8720

; #define LAS __attribute__((address_space(3)))
; #define ATT_LOADC(K0) do { _Pragma("unroll") for (int jj_ = 0; jj_ < 8; ++jj_) { int tok_ = (((K0) + 4 * jj_ + g16) << 4) + rho; tok_ = tok_ < SEQ - 1 ? tok_ : SEQ - 1; \
;         kst[jj_] = *(const u32x4*)(kbase + (size_t)tok_ * LDP + 8 * i16); vst[jj_] = *(const u32x4*)(vbase + (size_t)tok_ * LDP + 8 * i16); } } while (0)
; __device__ __forceinline__ void att_tile(const LAS unsigned char* kb, const LAS unsigned char* vb, int k0, int lq, int i, int hh, int troff,
;                                          const bf16x8 (&qf)[8], f32x16 (&oacc)[4], float& mrun, float& lrun) {
;     constexpr float SC = 0.08838834764831845f * 1.4426950408889634f;
;     f32x16 sacc, sacc2;
; #pragma unroll
;     for (int r = 0; r < 16; ++r) { sacc[r] = 0.f; sacc2[r] = 0.f; }
; #pragma unroll
;     for (int s = 0; s < 8; s += 2) { sacc = __builtin_amdgcn_mfma_f32_32x32x16_bf16(*(const LAS bf16x8*)(kb + i * 272 + 32 * s + 16 * hh), qf[s], sacc, 0, 0, 0);
;         sacc2 = __builtin_amdgcn_mfma_f32_32x32x16_bf16(*(const LAS bf16x8*)(kb + i * 272 + 32 * (s + 1) + 16 * hh), qf[s + 1], sacc2, 0, 0, 0); }
; #pragma unroll
;     for (int r = 0; r < 16; ++r) sacc[r] += sacc2[r];
;     float tmax = -1e30f;
;     const int dbase = lq - k0 - 4 * hh;
; #pragma unroll
;     for (int r = 0; r < 16; ++r) { const unsigned dd = (unsigned)(dbase - ((r & 3) + 8 * (r >> 2)));
;         const float sv = dd <= 128u ? sacc[r] * SC : -INFINITY; sacc[r] = sv; tmax = fmaxf(tmax, sv); }
; __device__ __forceinline__ void attn_wg(const bf16* PROJ, bf16* CONCAT, int wu, LAS unsigned char* L, int tid, int lane, int wave) {
;     ...
;       for (int j = 0; j < nt; ++j) {
;           ATT_LOADC(kC + 32 * j);
; #pragma unroll
;           for (int jj = 0; jj < 8; ++jj) { *(LAS u32x4*)(wb + (4 * jj + g16) * 272 + i16 * 16) = kst[jj]; *(LAS u32x4*)(wb + ATT_KS_BYTES + (4 * jj + g16) * 320 + i16 * 16) = vst[jj]; }
;           att_tile(wb, wb + ATT_KS_BYTES, kC + 32 * j, lq, i, hh, troff, qf, oacc, mrun, lrun);
.LBB0_677:
	v_min_i32_e32 v68, 0x7ff, v133
	v_mad_i64_i32 v[64:65], s[4:5], v68, s91, v[128:129]
	v_add_u32_e32 v72, 64, v133
	global_load_dwordx4 v[64:67], v[64:65], off
	v_mad_i64_i32 v[68:69], s[4:5], v68, s91, v[130:131]
	v_min_i32_e32 v76, 0x7ff, v72
	global_load_dwordx4 v[68:71], v[68:69], off
	v_mad_i64_i32 v[72:73], s[4:5], v76, s91, v[128:129]
	v_add_u32_e32 v80, 0x80, v133
	global_load_dwordx4 v[72:75], v[72:73], off
	v_mad_i64_i32 v[76:77], s[4:5], v76, s91, v[130:131]
	v_min_i32_e32 v84, 0x7ff, v80
	global_load_dwordx4 v[76:79], v[76:77], off
	v_mad_i64_i32 v[80:81], s[4:5], v84, s91, v[128:129]
	v_add_u32_e32 v88, 0xc0, v133
	v_add_u32_e32 v140, 0x100, v133
	global_load_dwordx4 v[80:83], v[80:81], off
	v_mad_i64_i32 v[84:85], s[4:5], v84, s91, v[130:131]
	v_min_i32_e32 v92, 0x7ff, v88
	v_min_i32_e32 v146, 0x7ff, v140
	global_load_dwordx4 v[84:87], v[84:85], off
	v_mad_i64_i32 v[88:89], s[4:5], v92, s91, v[128:129]
	v_mad_i64_i32 v[140:141], s[4:5], v146, s91, v[128:129]
	v_mad_i64_i32 v[148:149], s[4:5], v146, s91, v[130:131]
	v_add_u32_e32 v146, 0x140, v133
	global_load_dwordx4 v[88:91], v[88:89], off
	v_mad_i64_i32 v[92:93], s[4:5], v92, s91, v[130:131]
	v_min_i32_e32 v146, 0x7ff, v146
	global_load_dwordx4 v[92:95], v[92:93], off
	v_mad_i64_i32 v[152:153], s[4:5], v146, s91, v[128:129]
	global_load_dwordx4 v[140:143], v[140:141], off
	s_nop 0
	global_load_dwordx4 v[148:151], v[148:149], off
	s_nop 0
	global_load_dwordx4 v[156:159], v[152:153], off
	v_mad_i64_i32 v[152:153], s[4:5], v146, s91, v[130:131]
	v_add_u32_e32 v146, 0x180, v133
	v_min_i32_e32 v146, 0x7ff, v146
	global_load_dwordx4 v[172:175], v[152:153], off
	v_mad_i64_i32 v[152:153], s[4:5], v146, s91, v[128:129]
	global_load_dwordx4 v[176:179], v[152:153], off
	v_mad_i64_i32 v[152:153], s[4:5], v146, s91, v[130:131]
	v_add_u32_e32 v146, 0x1c0, v133
	v_min_i32_e32 v146, 0x7ff, v146
	global_load_dwordx4 v[180:183], v[152:153], off
	v_mad_i64_i32 v[152:153], s[4:5], v146, s91, v[128:129]
	global_load_dwordx4 v[186:189], v[152:153], off
	v_mad_i64_i32 v[152:153], s[4:5], v146, s91, v[130:131]
	global_load_dwordx4 v[190:193], v[152:153], off
	v_add_u32_e32 v133, 0x200, v133
	s_waitcnt vmcnt(15)
	ds_write_b128 v137, v[64:67]
	s_waitcnt vmcnt(14)
	ds_write_b128 v138, v[68:71] offset:8704
	s_waitcnt vmcnt(13)
	ds_write_b128 v137, v[72:75] offset:1088
	s_waitcnt vmcnt(12)
	ds_write_b128 v138, v[76:79] offset:9984
	s_waitcnt vmcnt(11)
	ds_write_b128 v137, v[80:83] offset:2176
	s_waitcnt vmcnt(10)
	ds_write_b128 v138, v[84:87] offset:11264
	s_waitcnt vmcnt(9)
	ds_write_b128 v137, v[88:91] offset:3264
	s_waitcnt vmcnt(8)
	ds_write_b128 v138, v[92:95] offset:12544
	s_waitcnt vmcnt(7)
	ds_write_b128 v137, v[140:143] offset:4352
	s_waitcnt vmcnt(6)
	ds_write_b128 v138, v[148:151] offset:13824
	s_waitcnt vmcnt(5)
	ds_write_b128 v137, v[156:159] offset:5440
	s_waitcnt vmcnt(4)
	ds_write_b128 v138, v[172:175] offset:15104
	s_waitcnt vmcnt(3)
	ds_write_b128 v137, v[176:179] offset:6528
	s_waitcnt vmcnt(2)
	ds_write_b128 v138, v[180:183] offset:16384
	s_waitcnt vmcnt(1)
	ds_write_b128 v137, v[186:189] offset:7616
	s_waitcnt vmcnt(0)
	ds_write_b128 v138, v[190:193] offset:17664
	ds_read_b128 v[64:67], v139
	ds_read_b128 v[80:83], v139 offset:32
	ds_read_b128 v[140:143], v139 offset:64
	ds_read_b128 v[222:225], v139 offset:96
	s_waitcnt lgkmcnt(1)
	v_mfma_f32_32x32x16_bf16 v[64:79], v[64:67], v[96:99], 0
	v_mfma_f32_32x32x16_bf16 v[64:79], v[140:143], v[104:107], v[64:79]
	ds_read_b128 v[140:143], v139 offset:128
	v_mfma_f32_32x32x16_bf16 v[80:95], v[80:83], v[100:103], 0
	s_waitcnt lgkmcnt(1)
	v_mfma_f32_32x32x16_bf16 v[80:95], v[222:225], v[108:111], v[80:95]
	ds_read_b128 v[222:225], v139 offset:160
	s_waitcnt lgkmcnt(1)
	v_mfma_f32_32x32x16_bf16 v[64:79], v[140:143], v[112:115], v[64:79]
	ds_read_b128 v[140:143], v139 offset:192
	s_waitcnt lgkmcnt(1)
	v_mfma_f32_32x32x16_bf16 v[80:95], v[222:225], v[116:119], v[80:95]
	ds_read_b128 v[222:225], v139 offset:224
	s_waitcnt lgkmcnt(1)
	v_mfma_f32_32x32x16_bf16 v[64:79], v[140:143], v[120:123], v[64:79]
	s_waitcnt lgkmcnt(0)
	v_mfma_f32_32x32x16_bf16 v[80:95], v[222:225], v[124:127], v[80:95]
	s_nop 11
	v_add_f32_e32 v64, v64, v80
	v_add_u32_e32 v80, 27, v134
	v_add_f32_e32 v65, v65, v81
	v_cmp_gt_u32_e32 vcc, s87, v80
	v_mul_f32_e32 v64, 0x3e0293ee, v64
	v_add_f32_e32 v66, v66, v82
	v_cndmask_b32_e32 v81, v167, v64, vcc
	v_cmp_lt_u32_e32 vcc, s22, v135
	v_mul_f32_e32 v64, 0x3e0293ee, v65
	v_add_u32_e32 v80, 25, v134
	v_add_f32_e32 v67, v67, v83
	v_cndmask_b32_e32 v65, v167, v64, vcc
	v_cmp_gt_u32_e32 vcc, s87, v80
	v_mul_f32_e32 v66, 0x3e0293ee, v66
	v_add_u32_e32 v80, 24, v134
	v_add_f32_e32 v68, v68, v84
	v_cndmask_b32_e32 v66, v167, v66, vcc
	v_cmp_gt_u32_e32 vcc, s87, v80
	v_mul_f32_e32 v67, 0x3e0293ee, v67
	v_add_u32_e32 v80, 19, v134
	v_add_f32_e32 v69, v69, v85
	v_cndmask_b32_e32 v67, v167, v67, vcc
	v_cmp_gt_u32_e32 vcc, s87, v80
	v_mul_f32_e32 v68, 0x3e0293ee, v68
	v_add_u32_e32 v80, 18, v134
	v_add_f32_e32 v70, v70, v86
	v_cndmask_b32_e32 v68, v167, v68, vcc
	v_cmp_gt_u32_e32 vcc, s87, v80
	v_mul_f32_e32 v69, 0x3e0293ee, v69
	v_add_u32_e32 v80, 17, v134
	v_add_f32_e32 v71, v71, v87
	v_cndmask_b32_e32 v69, v167, v69, vcc
	v_cmp_gt_u32_e32 vcc, s87, v80
	v_mul_f32_e32 v70, 0x3e0293ee, v70
	v_add_u32_e32 v80, 16, v134
	v_add_f32_e32 v72, v72, v88
	v_cndmask_b32_e32 v70, v167, v70, vcc
	v_cmp_gt_u32_e32 vcc, s87, v80
	v_mul_f32_e32 v71, 0x3e0293ee, v71
	v_add_u32_e32 v80, 11, v134
	v_add_f32_e32 v73, v73, v89
	v_cndmask_b32_e32 v71, v167, v71, vcc
	v_cmp_gt_u32_e32 vcc, s87, v80
	v_mul_f32_e32 v72, 0x3e0293ee, v72
; #define LAS __attribute__((address_space(3)))
; __device__ __forceinline__ bf16x8 pack_step(const f32x16& x, int s) { u32x4 p; p.x = cvtpk_c(x[8 * s], x[8 * s + 1]); p.y = cvtpk_c(x[8 * s + 2], x[8 * s + 3]); p.z = cvtpk_c(x[8 * s + 4], x[8 * s + 5]); p.w = cvtpk_c(x[8 * s + 6], x[8 * s + 7]); return __builtin_bit_cast(bf16x8, p); }
; #define ATT_TR4(O0, O1, O2, O3) asm volatile("ds_read_b64_tr_b16 %0, %4 offset:" #O0 "\n\tds_read_b64_tr_b16 %1, %4 offset:" #O1 "\n\tds_read_b64_tr_b16 %2, %4 offset:" #O2 "\n\tds_read_b64_tr_b16 %3, %4 offset:" #O3 "\n\ts_waitcnt lgkmcnt(0)" \
;         : "=&v"(a0), "=&v"(a1), "=&v"(a2), "=&v"(a3) : "v"(vp) : "memory")
; __device__ __forceinline__ void att_tile(const LAS unsigned char* kb, const LAS unsigned char* vb, int k0, int lq, int i, int hh, int troff,
;                                          const bf16x8 (&qf)[8], f32x16 (&oacc)[4], float& mrun, float& lrun) {
;     ...
;     float tmax = -1e30f;
;     const int dbase = lq - k0 - 4 * hh;
; #pragma unroll
;     for (int r = 0; r < 16; ++r) { const unsigned dd = (unsigned)(dbase - ((r & 3) + 8 * (r >> 2)));
;         const float sv = dd <= 128u ? sacc[r] * SC : -INFINITY; sacc[r] = sv; tmax = fmaxf(tmax, sv); }
;     { const u32x2 sw = __builtin_amdgcn_permlane32_swap(__float_as_uint(tmax), __float_as_uint(tmax), false, false); tmax = fmaxf(__uint_as_float(sw.x), __uint_as_float(sw.y)); }
;     const float mnew = fmaxf(mrun, tmax);
;     const float alpha = __builtin_amdgcn_exp2f(mrun - mnew);
; #pragma unroll
;     for (int dt = 0; dt < 4; ++dt)
; #pragma unroll
;         for (int r = 0; r < 16; ++r) oacc[dt][r] *= alpha;
;     float psum = 0.f;
; #pragma unroll
;     for (int r = 0; r < 16; ++r) { const float p = __builtin_amdgcn_exp2f(sacc[r] - mnew); sacc[r] = p; psum += p; }
;     { const u32x2 sw = __builtin_amdgcn_permlane32_swap(__float_as_uint(psum), __float_as_uint(psum), false, false); psum = __uint_as_float(sw.x) + __uint_as_float(sw.y); }
;     lrun = lrun * alpha + psum; mrun = mnew;
;     const bf16x8 pf0 = pack_step(sacc, 0), pf1 = pack_step(sacc, 1);
;     { const LAS unsigned char* vp = vb + troff;
;       v4i16_t a0, a1, a2, a3;
;     ...
;       ATT_TR4(0, 2560, 5120, 7680); ATT_PV(0);
;       ATT_TR4(64, 2624, 5184, 7744); ATT_PV(1);
;       ATT_TR4(128, 2688, 5248, 7808); ATT_PV(2);
;       ATT_TR4(192, 2752, 5312, 7872); ATT_PV(3);
	v_add_u32_e32 v80, 10, v134
	v_add_f32_e32 v74, v74, v90
	v_cndmask_b32_e32 v72, v167, v72, vcc
	v_cmp_gt_u32_e32 vcc, s87, v80
	v_mul_f32_e32 v73, 0x3e0293ee, v73
	v_add_u32_e32 v80, 9, v134
	v_add_f32_e32 v75, v75, v91
	v_max3_f32 v64, v81, s23, v65
	v_cndmask_b32_e32 v73, v167, v73, vcc
	v_cmp_gt_u32_e32 vcc, s87, v80
	v_mul_f32_e32 v74, 0x3e0293ee, v74
	v_add_u32_e32 v80, 8, v134
	v_add_f32_e32 v76, v76, v92
	v_max3_f32 v64, v64, v66, v67
	v_cndmask_b32_e32 v74, v167, v74, vcc
	v_cmp_gt_u32_e32 vcc, s87, v80
	v_mul_f32_e32 v75, 0x3e0293ee, v75
	v_add_u32_e32 v80, 3, v134
	v_add_f32_e32 v77, v77, v93
	v_max3_f32 v64, v64, v68, v69
	v_cndmask_b32_e32 v75, v167, v75, vcc
	v_cmp_gt_u32_e32 vcc, s87, v80
	v_mul_f32_e32 v76, 0x3e0293ee, v76
	v_add_u32_e32 v80, 2, v134
	v_add_f32_e32 v78, v78, v94
	v_max3_f32 v64, v64, v70, v71
	v_cndmask_b32_e32 v76, v167, v76, vcc
	v_cmp_gt_u32_e32 vcc, s87, v80
	v_mul_f32_e32 v77, 0x3e0293ee, v77
	v_add_u32_e32 v80, 1, v134
	v_add_f32_e32 v79, v79, v95
	v_max3_f32 v64, v64, v72, v73
	v_cndmask_b32_e32 v77, v167, v77, vcc
	v_cmp_gt_u32_e32 vcc, s87, v80
	v_mul_f32_e32 v78, 0x3e0293ee, v78
	v_max3_f32 v64, v64, v74, v75
	v_cndmask_b32_e32 v78, v167, v78, vcc
	v_cmp_gt_u32_e32 vcc, s87, v134
	v_mul_f32_e32 v79, 0x3e0293ee, v79
	v_max3_f32 v64, v64, v76, v77
	v_cndmask_b32_e32 v79, v167, v79, vcc
	v_max3_f32 v64, v64, v78, v79
	v_mov_b32_e32 v80, v64
	s_nop 1
	v_permlane32_swap_b32_e32 v64, v80
	v_max3_f32 v80, v170, v64, v80
	v_sub_f32_e32 v64, v170, v80
	v_exp_f32_e32 v64, v64
	v_sub_f32_e32 v81, v81, v80
	v_exp_f32_e32 v81, v81
	v_sub_f32_e32 v66, v66, v80
	v_pk_mul_f32 v[62:63], v[62:63], v[64:65] op_sel_hi:[1,0]
	v_pk_mul_f32 v[60:61], v[60:61], v[64:65] op_sel_hi:[1,0]
	v_pk_mul_f32 v[58:59], v[58:59], v[64:65] op_sel_hi:[1,0]
	v_pk_mul_f32 v[56:57], v[56:57], v[64:65] op_sel_hi:[1,0]
	v_pk_mul_f32 v[54:55], v[54:55], v[64:65] op_sel_hi:[1,0]
	v_pk_mul_f32 v[52:53], v[52:53], v[64:65] op_sel_hi:[1,0]
	v_pk_mul_f32 v[50:51], v[50:51], v[64:65] op_sel_hi:[1,0]
	v_pk_mul_f32 v[48:49], v[48:49], v[64:65] op_sel_hi:[1,0]
	v_pk_mul_f32 v[46:47], v[46:47], v[64:65] op_sel_hi:[1,0]
	v_pk_mul_f32 v[44:45], v[44:45], v[64:65] op_sel_hi:[1,0]
	v_pk_mul_f32 v[42:43], v[42:43], v[64:65] op_sel_hi:[1,0]
	v_pk_mul_f32 v[40:41], v[40:41], v[64:65] op_sel_hi:[1,0]
	v_pk_mul_f32 v[38:39], v[38:39], v[64:65] op_sel_hi:[1,0]
	v_pk_mul_f32 v[36:37], v[36:37], v[64:65] op_sel_hi:[1,0]
	v_pk_mul_f32 v[34:35], v[34:35], v[64:65] op_sel_hi:[1,0]
	v_pk_mul_f32 v[32:33], v[32:33], v[64:65] op_sel_hi:[1,0]
	v_pk_mul_f32 v[30:31], v[30:31], v[64:65] op_sel_hi:[1,0]
	v_pk_mul_f32 v[28:29], v[28:29], v[64:65] op_sel_hi:[1,0]
	v_pk_mul_f32 v[26:27], v[26:27], v[64:65] op_sel_hi:[1,0]
	v_pk_mul_f32 v[24:25], v[24:25], v[64:65] op_sel_hi:[1,0]
	v_pk_mul_f32 v[22:23], v[22:23], v[64:65] op_sel_hi:[1,0]
	v_pk_mul_f32 v[20:21], v[20:21], v[64:65] op_sel_hi:[1,0]
	v_pk_mul_f32 v[18:19], v[18:19], v[64:65] op_sel_hi:[1,0]
	v_pk_mul_f32 v[16:17], v[16:17], v[64:65] op_sel_hi:[1,0]
	v_pk_mul_f32 v[14:15], v[14:15], v[64:65] op_sel_hi:[1,0]
	v_pk_mul_f32 v[12:13], v[12:13], v[64:65] op_sel_hi:[1,0]
	v_pk_mul_f32 v[10:11], v[10:11], v[64:65] op_sel_hi:[1,0]
	v_pk_mul_f32 v[8:9], v[8:9], v[64:65] op_sel_hi:[1,0]
	v_pk_mul_f32 v[6:7], v[6:7], v[64:65] op_sel_hi:[1,0]
	v_pk_mul_f32 v[4:5], v[4:5], v[64:65] op_sel_hi:[1,0]
	v_pk_mul_f32 v[2:3], v[2:3], v[64:65] op_sel_hi:[1,0]
	v_pk_mul_f32 v[0:1], v[0:1], v[64:65] op_sel_hi:[1,0]
	v_sub_f32_e32 v65, v65, v80
	v_exp_f32_e32 v65, v65
	v_exp_f32_e32 v66, v66
	v_sub_f32_e32 v67, v67, v80
	v_exp_f32_e32 v67, v67
	v_sub_f32_e32 v68, v68, v80
	v_add_f32_e32 v82, 0, v81
	v_exp_f32_e32 v68, v68
	v_sub_f32_e32 v69, v69, v80
	v_add_f32_e32 v82, v65, v82
	v_exp_f32_e32 v69, v69
	v_sub_f32_e32 v70, v70, v80
	v_add_f32_e32 v82, v66, v82
	v_exp_f32_e32 v70, v70
	v_sub_f32_e32 v71, v71, v80
	v_add_f32_e32 v82, v67, v82
	v_exp_f32_e32 v71, v71
	v_sub_f32_e32 v72, v72, v80
	v_add_f32_e32 v82, v68, v82
	v_exp_f32_e32 v72, v72
	v_sub_f32_e32 v73, v73, v80
	v_add_f32_e32 v82, v69, v82
	v_exp_f32_e32 v73, v73
	v_sub_f32_e32 v74, v74, v80
	v_add_f32_e32 v82, v70, v82
	v_exp_f32_e32 v74, v74
	v_sub_f32_e32 v75, v75, v80
	v_add_f32_e32 v82, v71, v82
	v_exp_f32_e32 v75, v75
	v_sub_f32_e32 v76, v76, v80
	v_add_f32_e32 v82, v72, v82
	v_exp_f32_e32 v76, v76
	v_sub_f32_e32 v77, v77, v80
	v_add_f32_e32 v82, v73, v82
	v_exp_f32_e32 v77, v77
	v_sub_f32_e32 v78, v78, v80
	v_add_f32_e32 v82, v74, v82
	v_exp_f32_e32 v78, v78
	v_sub_f32_e32 v79, v79, v80
	v_add_f32_e32 v82, v75, v82
	v_exp_f32_e32 v79, v79
	v_add_f32_e32 v82, v76, v82
	v_add_f32_e32 v82, v77, v82
	v_add_f32_e32 v82, v78, v82
	v_add_f32_e32 v82, v79, v82
	v_mov_b32_e32 v83, v82
	s_nop 1
	v_permlane32_swap_b32_e32 v82, v83
	v_add_f32_e32 v82, v82, v83
	v_mov_b32_e32 v83, v147
	v_mov_b32_e32 v147, v82
	v_fmac_f32_e32 v147, v83, v64
	v_cvt_pk_bf16_f32 v64, v81, v65
	v_cvt_pk_bf16_f32 v65, v66, v67
	v_cvt_pk_bf16_f32 v66, v68, v69
	v_cvt_pk_bf16_f32 v67, v70, v71
	v_cvt_pk_bf16_f32 v68, v72, v73
	v_cvt_pk_bf16_f32 v69, v74, v75
	v_cvt_pk_bf16_f32 v70, v76, v77
	v_cvt_pk_bf16_f32 v71, v78, v79
	ds_read_b64_tr_b16 v[76:77], v132 offset:0
	ds_read_b64_tr_b16 v[78:79], v132 offset:2560
	ds_read_b64_tr_b16 v[72:73], v132 offset:5120
	ds_read_b64_tr_b16 v[74:75], v132 offset:7680
	ds_read_b64_tr_b16 v[214:215], v132 offset:64
	ds_read_b64_tr_b16 v[216:217], v132 offset:2624
	ds_read_b64_tr_b16 v[218:219], v132 offset:5184
	ds_read_b64_tr_b16 v[220:221], v132 offset:7744
	s_waitcnt lgkmcnt(4)
	v_add_co_u32_e32 v136, vcc, 1, v136
	v_mfma_f32_32x32x16_bf16 v[48:63], v[76:79], v[64:67], v[48:63]
	v_subrev_u32_e32 v134, 32, v134
	v_add_u32_e32 v135, 32, v135
	s_andn2_b64 vcc, exec, vcc
	v_mov_b32_e32 v170, v80
	v_mfma_f32_32x32x16_bf16 v[48:63], v[72:75], v[68:71], v[48:63]
	ds_read_b64_tr_b16 v[76:77], v132 offset:128
	ds_read_b64_tr_b16 v[78:79], v132 offset:2688
	ds_read_b64_tr_b16 v[72:73], v132 offset:5248
	ds_read_b64_tr_b16 v[74:75], v132 offset:7808
	s_waitcnt lgkmcnt(4)
	s_nop 0
	v_mfma_f32_32x32x16_bf16 v[32:47], v[214:217], v[64:67], v[32:47]
	v_mfma_f32_32x32x16_bf16 v[32:47], v[218:221], v[68:71], v[32:47]
	ds_read_b64_tr_b16 v[214:215], v132 offset:192
	ds_read_b64_tr_b16 v[216:217], v132 offset:2752
	ds_read_b64_tr_b16 v[218:219], v132 offset:5312
	ds_read_b64_tr_b16 v[220:221], v132 offset:7872
	s_waitcnt lgkmcnt(4)
	s_nop 0
	v_mfma_f32_32x32x16_bf16 v[16:31], v[76:79], v[64:67], v[16:31]
	v_mfma_f32_32x32x16_bf16 v[16:31], v[72:75], v[68:71], v[16:31]
	s_waitcnt lgkmcnt(0)
	s_nop 0
	v_mfma_f32_32x32x16_bf16 v[0:15], v[214:217], v[64:67], v[0:15]
	v_mfma_f32_32x32x16_bf16 v[0:15], v[218:221], v[68:71], v[0:15]
	s_cbranch_vccnz .LBB0_677
; __device__ __forceinline__ unsigned cvtpk_c(float lo, float hi) { f32x2 v = {lo, hi}; bf16x2_t b = __builtin_convertvector(v, bf16x2_t); return __builtin_bit_cast(unsigned, b); }
; __device__ __forceinline__ void attn_wg(const bf16* PROJ, bf16* CONCAT, int wu, LAS unsigned char* L, int tid, int lane, int wave) {
;     ...
;     const float inv = 1.0f / lrun;
;     bf16* op = CONCAT + (rowbase + tq) * LDD + h * HD + 8 * hh;
; #pragma unroll
;     for (int dt = 0; dt < 4; ++dt)
; #pragma unroll
;         for (int k = 0; k < 2; ++k) { const int g0 = 8 * k, g1 = 8 * k + 4;
;             const unsigned a0 = cvtpk_c(oacc[dt][g0] * inv, oacc[dt][g0 + 1] * inv), a1 = cvtpk_c(oacc[dt][g0 + 2] * inv, oacc[dt][g0 + 3] * inv);
;             const unsigned b0 = cvtpk_c(oacc[dt][g1] * inv, oacc[dt][g1 + 1] * inv), b1 = cvtpk_c(oacc[dt][g1 + 2] * inv, oacc[dt][g1 + 3] * inv);
;             const u32x2 s0 = __builtin_amdgcn_permlane32_swap(a0, b0, false, false), s1 = __builtin_amdgcn_permlane32_swap(a1, b1, false, false);
;             u32x4 w; w.x = s0.x; w.y = s1.x; w.z = s0.y; w.w = s1.y;
;             *(u32x4*)(op + 32 * dt + 16 * k) = w; }
	v_div_scale_f32 v64, s[4:5], v147, v147, 1.0
	v_rcp_f32_e32 v65, v64
	v_div_scale_f32 v66, vcc, 1.0, v147, 1.0
	s_movk_i32 s4, 0x2080
	v_fma_f32 v67, -v64, v65, 1.0
	v_fmac_f32_e32 v65, v67, v65
	v_mul_f32_e32 v67, v66, v65
	v_fma_f32 v68, -v64, v67, v66
	v_fmac_f32_e32 v67, v68, v65
	v_fma_f32 v64, -v64, v67, v66
	v_div_fmas_f32 v64, v64, v65, v67
	v_div_fixup_f32 v64, v64, v147, 1.0
	v_mov_b64_e32 v[66:67], s[40:41]
	v_pk_mul_f32 v[48:49], v[48:49], v[64:65] op_sel_hi:[1,0]
	v_pk_mul_f32 v[50:51], v[50:51], v[64:65] op_sel_hi:[1,0]
	v_pk_mul_f32 v[32:33], v[32:33], v[64:65] op_sel_hi:[1,0]
	v_pk_mul_f32 v[34:35], v[34:35], v[64:65] op_sel_hi:[1,0]
	v_pk_mul_f32 v[16:17], v[64:65], v[16:17] op_sel_hi:[0,1]
	v_pk_mul_f32 v[18:19], v[64:65], v[18:19] op_sel_hi:[0,1]
	v_pk_mul_f32 v[0:1], v[64:65], v[0:1] op_sel_hi:[0,1]
	v_pk_mul_f32 v[2:3], v[64:65], v[2:3] op_sel_hi:[0,1]
	v_mad_u64_u32 v[66:67], s[4:5], v154, s4, v[66:67]
	v_cvt_pk_bf16_f32 v48, v48, v49
	v_cvt_pk_bf16_f32 v49, v50, v51
	v_pk_mul_f32 v[50:51], v[52:53], v[64:65] op_sel_hi:[1,0]
	v_pk_mul_f32 v[52:53], v[54:55], v[64:65] op_sel_hi:[1,0]
	v_cvt_pk_bf16_f32 v32, v32, v33
	v_cvt_pk_bf16_f32 v33, v34, v35
	v_pk_mul_f32 v[34:35], v[36:37], v[64:65] op_sel_hi:[1,0]
	v_pk_mul_f32 v[36:37], v[38:39], v[64:65] op_sel_hi:[1,0]
	v_cvt_pk_bf16_f32 v16, v16, v17
	v_cvt_pk_bf16_f32 v17, v18, v19
	v_pk_mul_f32 v[18:19], v[64:65], v[20:21] op_sel_hi:[0,1]
	v_pk_mul_f32 v[20:21], v[64:65], v[22:23] op_sel_hi:[0,1]
	v_cvt_pk_bf16_f32 v0, v0, v1
	v_cvt_pk_bf16_f32 v1, v2, v3
	v_pk_mul_f32 v[2:3], v[64:65], v[4:5] op_sel_hi:[0,1]
	v_pk_mul_f32 v[4:5], v[64:65], v[6:7] op_sel_hi:[0,1]
	v_lshl_add_u64 v[66:67], v[66:67], 0, s[42:43]
	v_cvt_pk_bf16_f32 v50, v50, v51
	v_cvt_pk_bf16_f32 v51, v52, v53
	v_cvt_pk_bf16_f32 v34, v34, v35
	v_cvt_pk_bf16_f32 v35, v36, v37
	v_cvt_pk_bf16_f32 v18, v18, v19
	v_cvt_pk_bf16_f32 v19, v20, v21
	v_cvt_pk_bf16_f32 v2, v2, v3
	v_cvt_pk_bf16_f32 v3, v4, v5
	v_lshl_add_u64 v[66:67], v[144:145], 1, v[66:67]
	v_permlane32_swap_b32_e32 v48, v50
	v_permlane32_swap_b32_e32 v49, v51
	v_permlane32_swap_b32_e32 v32, v34
	v_permlane32_swap_b32_e32 v33, v35
	v_permlane32_swap_b32_e32 v16, v18
	v_permlane32_swap_b32_e32 v17, v19
	v_permlane32_swap_b32_e32 v0, v2
	v_permlane32_swap_b32_e32 v1, v3
	global_store_dwordx4 v[66:67], v[48:51], off
	global_store_dwordx4 v[66:67], v[32:35], off offset:64
	global_store_dwordx4 v[66:67], v[16:19], off offset:128
	v_pk_mul_f32 v[48:49], v[56:57], v[64:65] op_sel_hi:[1,0]
	v_pk_mul_f32 v[50:51], v[58:59], v[64:65] op_sel_hi:[1,0]
	v_pk_mul_f32 v[32:33], v[40:41], v[64:65] op_sel_hi:[1,0]
	v_pk_mul_f32 v[34:35], v[42:43], v[64:65] op_sel_hi:[1,0]
	v_pk_mul_f32 v[16:17], v[64:65], v[24:25] op_sel_hi:[0,1]
	v_pk_mul_f32 v[18:19], v[64:65], v[26:27] op_sel_hi:[0,1]
	global_store_dwordx4 v[66:67], v[0:3], off offset:192
	v_cvt_pk_bf16_f32 v48, v48, v49
	v_cvt_pk_bf16_f32 v49, v50, v51
	v_pk_mul_f32 v[0:1], v[64:65], v[8:9] op_sel_hi:[0,1]
	v_pk_mul_f32 v[2:3], v[64:65], v[10:11] op_sel_hi:[0,1]
	v_pk_mul_f32 v[50:51], v[60:61], v[64:65] op_sel_hi:[1,0]
	v_pk_mul_f32 v[52:53], v[62:63], v[64:65] op_sel_hi:[1,0]
	v_cvt_pk_bf16_f32 v32, v32, v33
	v_cvt_pk_bf16_f32 v33, v34, v35
	v_pk_mul_f32 v[34:35], v[44:45], v[64:65] op_sel_hi:[1,0]
	v_pk_mul_f32 v[36:37], v[46:47], v[64:65] op_sel_hi:[1,0]
	v_cvt_pk_bf16_f32 v16, v16, v17
	v_cvt_pk_bf16_f32 v17, v18, v19
	v_pk_mul_f32 v[18:19], v[64:65], v[28:29] op_sel_hi:[0,1]
	v_pk_mul_f32 v[20:21], v[64:65], v[30:31] op_sel_hi:[0,1]
	v_cvt_pk_bf16_f32 v0, v0, v1
	v_cvt_pk_bf16_f32 v1, v2, v3
	v_pk_mul_f32 v[2:3], v[64:65], v[12:13] op_sel_hi:[0,1]
	v_pk_mul_f32 v[4:5], v[64:65], v[14:15] op_sel_hi:[0,1]
	v_cvt_pk_bf16_f32 v50, v50, v51
	v_cvt_pk_bf16_f32 v51, v52, v53
	v_cvt_pk_bf16_f32 v34, v34, v35
	v_cvt_pk_bf16_f32 v35, v36, v37
	v_cvt_pk_bf16_f32 v18, v18, v19
	v_cvt_pk_bf16_f32 v19, v20, v21
	v_cvt_pk_bf16_f32 v2, v2, v3
	v_cvt_pk_bf16_f32 v3, v4, v5
	v_permlane32_swap_b32_e32 v48, v50
	v_permlane32_swap_b32_e32 v49, v51
	v_permlane32_swap_b32_e32 v32, v34
	v_permlane32_swap_b32_e32 v33, v35
	v_permlane32_swap_b32_e32 v16, v18
	v_permlane32_swap_b32_e32 v17, v19
	v_permlane32_swap_b32_e32 v0, v2
	v_permlane32_swap_b32_e32 v1, v3
	global_store_dwordx4 v[66:67], v[48:51], off offset:32
	global_store_dwordx4 v[66:67], v[32:35], off offset:96
	global_store_dwordx4 v[66:67], v[16:19], off offset:160
	global_store_dwordx4 v[66:67], v[0:3], off offset:224
	s_mov_b64 s[4:5], 0
